# attention: end-of-item barrier moved into the next item's staging, just before its first shared-LDS (K tile) write; exit path keeps its own barrier
# speedup vs baseline: 1.0038x; 1.0033x over previous
.LBB0_347:
	v_cndmask_b32_e64 v72, v48, v212, s[2:3]
	v_cndmask_b32_e64 v167, v72, v48, s[4:5]
	v_max3_f32 v48, v98, s64, v105
	v_max3_f32 v48, v48, v104, v103
	v_max3_f32 v48, v48, v102, v101
	v_max3_f32 v48, v48, v100, v99
	v_max3_f32 v48, v48, v71, v70
	v_max3_f32 v48, v48, v69, v68
	v_max3_f32 v48, v48, v67, v66
	v_max3_f32 v48, v48, v65, v64
	v_max3_f32 v48, v48, v32, v33
	v_max3_f32 v48, v48, v34, v35
	v_max3_f32 v48, v48, v36, v37
	v_max3_f32 v48, v48, v38, v39
	v_max3_f32 v48, v48, v40, v41
	v_max3_f32 v48, v48, v42, v43
	v_max3_f32 v48, v48, v44, v45
	v_max3_f32 v48, v48, v46, v47
	v_max3_f32 v48, v48, v16, v17
	v_max3_f32 v48, v48, v18, v19
	v_max3_f32 v48, v48, v20, v21
	v_max3_f32 v48, v48, v22, v23
	v_max3_f32 v48, v48, v24, v25
	v_max3_f32 v48, v48, v26, v27
	v_max3_f32 v48, v48, v28, v29
	v_max3_f32 v48, v48, v30, v31
	v_max3_f32 v48, v48, v0, v1
	v_max3_f32 v48, v48, v2, v3
	v_max3_f32 v48, v48, v4, v5
	v_max3_f32 v48, v48, v6, v7
	v_max3_f32 v48, v48, v8, v9
	v_max3_f32 v48, v48, v10, v11
	v_max3_f32 v48, v48, v12, v13
	v_cndmask_b32_e64 v166, v212, v49, s[4:5]
	v_max3_f32 v48, v48, v14, v15
	v_cndmask_b32_e64 v168, v50, v212, s[6:7]
	v_cndmask_b32_e64 v169, v51, v212, s[8:9]
	v_max3_f32 v48, v48, v167, v166
	v_cndmask_b32_e64 v170, v52, v212, s[10:11]
	v_cndmask_b32_e64 v171, v53, v212, s[12:13]
	v_max3_f32 v48, v48, v168, v169
	v_cndmask_b32_e64 v172, v54, v212, s[14:15]
	v_cndmask_b32_e64 v173, v55, v212, s[16:17]
	v_max3_f32 v48, v48, v170, v171
	v_cndmask_b32_e64 v174, v56, v212, s[18:19]
	v_cndmask_b32_e64 v175, v57, v212, s[20:21]
	v_max3_f32 v48, v48, v172, v173
	v_cndmask_b32_e64 v176, v58, v212, s[22:23]
	v_cndmask_b32_e64 v177, v59, v212, s[24:25]
	v_max3_f32 v48, v48, v174, v175
	v_cndmask_b32_e64 v178, v60, v212, s[26:27]
	v_cndmask_b32_e64 v179, v61, v212, s[28:29]
	v_max3_f32 v48, v48, v176, v177
	v_cndmask_b32_e64 v180, v62, v212, s[30:31]
	v_cndmask_b32_e64 v181, v63, v212, s[34:35]
	v_max3_f32 v48, v48, v178, v179
	v_max3_f32 v48, v48, v180, v181
	ds_bpermute_b32 v49, v188, v48
	v_or_b32_e32 v153, s89, v118
	v_readlane_b32 s0, v255, 16
	s_add_i32 s96, s96, s1
	s_add_i32 s90, s90, s0
	s_waitcnt lgkmcnt(0)
	v_max3_f32 v213, v48, v49, v96
	v_sub_f32_e32 v50, v104, v213
	v_exp_f32_e32 v154, v50
	v_sub_f32_e32 v50, v103, v213
	v_exp_f32_e32 v155, v50
	v_sub_f32_e32 v50, v102, v213
	v_exp_f32_e32 v160, v50
	v_sub_f32_e32 v50, v101, v213
	v_exp_f32_e32 v161, v50
	v_sub_f32_e32 v50, v100, v213
	v_sub_f32_e32 v48, v98, v213
	v_exp_f32_e32 v164, v50
	v_sub_f32_e32 v50, v99, v213
	v_exp_f32_e32 v110, v48
	v_sub_f32_e32 v48, v105, v213
	v_exp_f32_e32 v165, v50
	v_sub_f32_e32 v50, v71, v213
	v_exp_f32_e32 v111, v48
	v_exp_f32_e32 v102, v50
	v_sub_f32_e32 v50, v70, v213
	v_exp_f32_e32 v103, v50
	v_sub_f32_e32 v50, v69, v213
	v_sub_f32_e32 v34, v34, v213
	v_exp_f32_e32 v112, v50
	v_sub_f32_e32 v50, v68, v213
	v_exp_f32_e32 v106, v34
	v_sub_f32_e32 v34, v35, v213
	v_exp_f32_e32 v113, v50
	v_sub_f32_e32 v50, v67, v213
	v_exp_f32_e32 v107, v34
	v_sub_f32_e32 v34, v36, v213
	v_pk_add_f32 v[48:49], v[110:111], 0 op_sel_hi:[1,0]
	v_exp_f32_e32 v156, v50
	v_sub_f32_e32 v50, v66, v213
	v_exp_f32_e32 v118, v34
	v_sub_f32_e32 v34, v37, v213
	v_pk_add_f32 v[48:49], v[154:155], v[48:49]
	v_exp_f32_e32 v157, v50
	v_sub_f32_e32 v50, v65, v213
	v_exp_f32_e32 v119, v34
	v_sub_f32_e32 v34, v38, v213
	v_pk_add_f32 v[48:49], v[160:161], v[48:49]
	v_exp_f32_e32 v162, v50
	v_sub_f32_e32 v50, v64, v213
	v_sub_f32_e32 v32, v32, v213
	v_exp_f32_e32 v158, v34
	v_sub_f32_e32 v34, v39, v213
	v_pk_add_f32 v[48:49], v[164:165], v[48:49]
	v_exp_f32_e32 v163, v50
	v_exp_f32_e32 v78, v32
	v_sub_f32_e32 v32, v33, v213
	v_exp_f32_e32 v159, v34
	v_sub_f32_e32 v34, v40, v213
	v_pk_add_f32 v[48:49], v[102:103], v[48:49]
	v_exp_f32_e32 v79, v32
	v_exp_f32_e32 v68, v34
	v_sub_f32_e32 v34, v41, v213
	v_pk_add_f32 v[48:49], v[112:113], v[48:49]
	v_exp_f32_e32 v69, v34
	v_sub_f32_e32 v34, v42, v213
	v_sub_f32_e32 v18, v18, v213
	v_sub_f32_e32 v2, v2, v213
	v_pk_add_f32 v[48:49], v[156:157], v[48:49]
	v_exp_f32_e32 v76, v34
	v_sub_f32_e32 v34, v43, v213
	v_exp_f32_e32 v72, v18
	v_sub_f32_e32 v18, v19, v213
	v_exp_f32_e32 v60, v2
	v_sub_f32_e32 v2, v3, v213
	v_pk_add_f32 v[48:49], v[162:163], v[48:49]
	v_exp_f32_e32 v77, v34
	v_sub_f32_e32 v34, v44, v213
	v_exp_f32_e32 v73, v18
	v_sub_f32_e32 v18, v20, v213
	v_exp_f32_e32 v61, v2
	v_sub_f32_e32 v2, v4, v213
	v_pk_add_f32 v[32:33], v[78:79], v[48:49]
	v_exp_f32_e32 v104, v34
	v_sub_f32_e32 v34, v45, v213
	v_exp_f32_e32 v100, v18
	v_sub_f32_e32 v18, v21, v213
	v_exp_f32_e32 v66, v2
	v_sub_f32_e32 v2, v5, v213
	v_pk_add_f32 v[32:33], v[106:107], v[32:33]
	v_exp_f32_e32 v105, v34
	v_sub_f32_e32 v34, v46, v213
	v_exp_f32_e32 v101, v18
	v_sub_f32_e32 v18, v22, v213
	v_exp_f32_e32 v67, v2
	v_sub_f32_e32 v2, v6, v213
	v_pk_add_f32 v[32:33], v[118:119], v[32:33]
	v_exp_f32_e32 v114, v34
	v_sub_f32_e32 v34, v47, v213
	v_sub_f32_e32 v16, v16, v213
	v_exp_f32_e32 v108, v18
	v_sub_f32_e32 v18, v23, v213
	v_exp_f32_e32 v74, v2
	v_sub_f32_e32 v2, v7, v213
	v_pk_add_f32 v[32:33], v[158:159], v[32:33]
	v_exp_f32_e32 v115, v34
	v_exp_f32_e32 v64, v16
	v_sub_f32_e32 v16, v17, v213
	v_exp_f32_e32 v109, v18
	v_sub_f32_e32 v18, v24, v213
	v_exp_f32_e32 v75, v2
	v_sub_f32_e32 v2, v8, v213
	v_pk_add_f32 v[32:33], v[68:69], v[32:33]
	v_exp_f32_e32 v65, v16
	v_exp_f32_e32 v58, v18
	v_sub_f32_e32 v18, v25, v213
	v_exp_f32_e32 v48, v2
	v_sub_f32_e32 v2, v9, v213
	v_pk_add_f32 v[32:33], v[76:77], v[32:33]
	v_exp_f32_e32 v59, v18
	v_sub_f32_e32 v18, v26, v213
	v_exp_f32_e32 v49, v2
	v_sub_f32_e32 v2, v10, v213
	v_pk_add_f32 v[32:33], v[104:105], v[32:33]
	v_exp_f32_e32 v62, v18
	v_sub_f32_e32 v18, v27, v213
	v_exp_f32_e32 v50, v2
	v_sub_f32_e32 v2, v11, v213
	v_pk_add_f32 v[32:33], v[114:115], v[32:33]
	v_exp_f32_e32 v63, v18
	v_sub_f32_e32 v18, v28, v213
	v_exp_f32_e32 v51, v2
	v_sub_f32_e32 v2, v12, v213
	v_pk_add_f32 v[16:17], v[64:65], v[32:33]
	v_exp_f32_e32 v70, v18
	v_sub_f32_e32 v18, v29, v213
	v_exp_f32_e32 v52, v2
	v_sub_f32_e32 v2, v13, v213
	v_pk_add_f32 v[16:17], v[72:73], v[16:17]
	v_exp_f32_e32 v71, v18
	v_sub_f32_e32 v18, v30, v213
	v_exp_f32_e32 v53, v2
	v_sub_f32_e32 v2, v14, v213
	v_pk_add_f32 v[16:17], v[100:101], v[16:17]
	v_exp_f32_e32 v98, v18
	v_sub_f32_e32 v18, v31, v213
	v_sub_f32_e32 v0, v0, v213
	v_exp_f32_e32 v54, v2
	v_sub_f32_e32 v2, v15, v213
	v_pk_add_f32 v[16:17], v[108:109], v[16:17]
	v_exp_f32_e32 v99, v18
	v_exp_f32_e32 v56, v0
	v_sub_f32_e32 v0, v1, v213
	v_exp_f32_e32 v55, v2
	v_sub_f32_e32 v2, v167, v213
	v_pk_add_f32 v[16:17], v[58:59], v[16:17]
	v_exp_f32_e32 v57, v0
	v_exp_f32_e32 v40, v2
	v_sub_f32_e32 v2, v166, v213
	v_pk_add_f32 v[16:17], v[62:63], v[16:17]
	v_exp_f32_e32 v41, v2
	v_sub_f32_e32 v2, v168, v213
	v_pk_add_f32 v[16:17], v[70:71], v[16:17]
	v_exp_f32_e32 v42, v2
	v_sub_f32_e32 v2, v169, v213
	v_pk_add_f32 v[16:17], v[98:99], v[16:17]
	v_exp_f32_e32 v43, v2
	v_sub_f32_e32 v2, v170, v213
	v_pk_add_f32 v[0:1], v[56:57], v[16:17]
	v_exp_f32_e32 v44, v2
	v_sub_f32_e32 v2, v171, v213
	v_pk_add_f32 v[0:1], v[60:61], v[0:1]
	v_exp_f32_e32 v45, v2
	v_sub_f32_e32 v2, v172, v213
	v_pk_add_f32 v[0:1], v[66:67], v[0:1]
	v_exp_f32_e32 v46, v2
	v_sub_f32_e32 v2, v173, v213
	v_pk_add_f32 v[0:1], v[74:75], v[0:1]
	v_exp_f32_e32 v47, v2
	v_sub_f32_e32 v2, v174, v213
	v_pk_add_f32 v[0:1], v[48:49], v[0:1]
	v_exp_f32_e32 v32, v2
	v_sub_f32_e32 v2, v175, v213
	v_pk_add_f32 v[0:1], v[50:51], v[0:1]
	v_exp_f32_e32 v33, v2
	v_sub_f32_e32 v2, v176, v213
	v_pk_add_f32 v[0:1], v[52:53], v[0:1]
	v_exp_f32_e32 v34, v2
	v_sub_f32_e32 v2, v177, v213
	v_pk_add_f32 v[0:1], v[54:55], v[0:1]
	v_exp_f32_e32 v35, v2
	v_sub_f32_e32 v2, v178, v213
	v_pk_add_f32 v[0:1], v[40:41], v[0:1]
	v_exp_f32_e32 v36, v2
	v_sub_f32_e32 v2, v179, v213
	v_pk_add_f32 v[0:1], v[42:43], v[0:1]
	v_exp_f32_e32 v37, v2
	v_sub_f32_e32 v2, v180, v213
	v_pk_add_f32 v[0:1], v[44:45], v[0:1]
	v_exp_f32_e32 v38, v2
	v_sub_f32_e32 v2, v181, v213
	v_pk_add_f32 v[0:1], v[46:47], v[0:1]
	v_exp_f32_e32 v39, v2
	v_pk_add_f32 v[0:1], v[32:33], v[0:1]
	v_cvt_pk_bf16_f32 v16, v110, v111
	v_cvt_pk_bf16_f32 v17, v154, v155
	v_add_u32_e32 v154, 0x9000, v207
	v_pk_add_f32 v[0:1], v[34:35], v[0:1]
	v_cvt_pk_bf16_f32 v18, v160, v161
	v_cvt_pk_bf16_f32 v19, v164, v165
	v_add_u32_e32 v160, 0xd000, v207
	v_pk_add_f32 v[0:1], v[36:37], v[0:1]
	ds_read2_b64 v[20:23], v160 offset0:32 offset1:34
	v_pk_add_f32 v[0:1], v[38:39], v[0:1]
	s_nop 0
	v_add_f32_e32 v0, v0, v1
	ds_bpermute_b32 v1, v188, v0
	s_waitcnt lgkmcnt(0)
	v_add_f32_e32 v0, v0, v1
	v_sub_f32_e32 v1, v96, v213
	v_exp_f32_e32 v1, v1
	s_nop 0
	v_add_f32_e32 v96, v1, v0
	ds_read2_b64 v[0:3], v154 offset1:2
	v_cvt_pk_bf16_f32 v110, v102, v103
	v_cvt_pk_bf16_f32 v111, v112, v113
	v_cvt_pk_bf16_f32 v112, v156, v157
	v_cvt_pk_bf16_f32 v113, v162, v163
	ds_read2_b64 v[154:157], v154 offset0:4 offset1:6
	s_waitcnt lgkmcnt(1)
	v_mfma_f32_32x32x16_bf16 v[0:15], v[0:3], v[16:19], 0
	s_waitcnt lgkmcnt(0)
	v_mfma_f32_32x32x16_bf16 v[0:15], v[154:157], v[110:113], v[0:15]
	ds_read2_b64 v[154:157], v160 offset0:36 offset1:38
	v_mfma_f32_32x32x16_bf16 v[16:31], v[20:23], v[16:19], 0
	s_waitcnt lgkmcnt(0)
	v_mfma_f32_32x32x16_bf16 v[16:31], v[154:157], v[110:113], v[16:31]
	v_cvt_pk_bf16_f32 v110, v78, v79
	v_add_u32_e32 v78, 0x9000, v208
	v_cvt_pk_bf16_f32 v111, v106, v107
	v_cvt_pk_bf16_f32 v112, v118, v119
	v_cvt_pk_bf16_f32 v113, v158, v159
	ds_read2_b64 v[154:157], v78 offset1:2
	v_add_u32_e32 v106, 0xd000, v208
	s_waitcnt lgkmcnt(0)
	v_mfma_f32_32x32x16_bf16 v[0:15], v[154:157], v[110:113], v[0:15]
	ds_read2_b64 v[154:157], v106 offset0:32 offset1:34
	v_cvt_pk_bf16_f32 v102, v68, v69
	v_cvt_pk_bf16_f32 v103, v76, v77
	v_cvt_pk_bf16_f32 v104, v104, v105
	v_cvt_pk_bf16_f32 v105, v114, v115
	ds_read2_b64 v[76:79], v78 offset0:4 offset1:6
	s_waitcnt lgkmcnt(0)
	v_mfma_f32_32x32x16_bf16 v[0:15], v[76:79], v[102:105], v[0:15]
	ds_read2_b64 v[76:79], v106 offset0:36 offset1:38
	v_mfma_f32_32x32x16_bf16 v[16:31], v[154:157], v[110:113], v[16:31]
	s_waitcnt lgkmcnt(0)
	v_mfma_f32_32x32x16_bf16 v[16:31], v[76:79], v[102:105], v[16:31]
	v_cvt_pk_bf16_f32 v76, v64, v65
	v_add_u32_e32 v64, 0x9000, v209
	v_cvt_pk_bf16_f32 v77, v72, v73
	v_cvt_pk_bf16_f32 v78, v100, v101
	v_cvt_pk_bf16_f32 v79, v108, v109
	ds_read2_b64 v[100:103], v64 offset1:2
	v_add_u32_e32 v72, 0xd000, v209
	s_waitcnt lgkmcnt(0)
	v_mfma_f32_32x32x16_bf16 v[0:15], v[100:103], v[76:79], v[0:15]
	ds_read2_b64 v[100:103], v72 offset0:32 offset1:34
	v_cvt_pk_bf16_f32 v68, v58, v59
	v_cvt_pk_bf16_f32 v69, v62, v63
	v_cvt_pk_bf16_f32 v70, v70, v71
	v_cvt_pk_bf16_f32 v71, v98, v99
	ds_read2_b64 v[62:65], v64 offset0:4 offset1:6
	s_waitcnt lgkmcnt(0)
	v_mfma_f32_32x32x16_bf16 v[0:15], v[62:65], v[68:71], v[0:15]
	ds_read2_b64 v[62:65], v72 offset0:36 offset1:38
	v_cvt_pk_bf16_f32 v56, v56, v57
	v_cvt_pk_bf16_f32 v57, v60, v61
	v_cvt_pk_bf16_f32 v58, v66, v67
	v_cvt_pk_bf16_f32 v59, v74, v75
	v_mfma_f32_32x32x16_bf16 v[16:31], v[100:103], v[76:79], v[16:31]
	s_waitcnt lgkmcnt(0)
	v_mfma_f32_32x32x16_bf16 v[16:31], v[62:65], v[68:71], v[16:31]
	v_add_u32_e32 v64, 0x9000, v210
	ds_read2_b64 v[60:63], v64 offset1:2
	v_add_u32_e32 v65, 0xd000, v210
	s_waitcnt lgkmcnt(0)
	v_mfma_f32_32x32x16_bf16 v[0:15], v[60:63], v[56:59], v[0:15]
	ds_read2_b64 v[60:63], v65 offset0:32 offset1:34
	v_cvt_pk_bf16_f32 v48, v48, v49
	v_cvt_pk_bf16_f32 v49, v50, v51
	v_cvt_pk_bf16_f32 v50, v52, v53
	v_cvt_pk_bf16_f32 v51, v54, v55
	ds_read2_b64 v[52:55], v64 offset0:4 offset1:6
	s_waitcnt lgkmcnt(0)
	v_mfma_f32_32x32x16_bf16 v[0:15], v[52:55], v[48:51], v[0:15]
	ds_read2_b64 v[52:55], v65 offset0:36 offset1:38
	v_cvt_pk_bf16_f32 v40, v40, v41
	v_cvt_pk_bf16_f32 v41, v42, v43
	v_cvt_pk_bf16_f32 v42, v44, v45
	v_cvt_pk_bf16_f32 v43, v46, v47
	v_mfma_f32_32x32x16_bf16 v[16:31], v[60:63], v[56:59], v[16:31]
	s_waitcnt lgkmcnt(0)
	v_mfma_f32_32x32x16_bf16 v[16:31], v[52:55], v[48:51], v[16:31]
	v_add_u32_e32 v48, 0x9000, v211
	ds_read2_b64 v[44:47], v48 offset1:2
	v_add_u32_e32 v49, 0xd000, v211
	s_waitcnt lgkmcnt(0)
	v_mfma_f32_32x32x16_bf16 v[0:15], v[44:47], v[40:43], v[0:15]
	ds_read2_b64 v[44:47], v49 offset0:32 offset1:34
	v_cvt_pk_bf16_f32 v32, v32, v33
	v_cvt_pk_bf16_f32 v33, v34, v35
	v_cvt_pk_bf16_f32 v34, v36, v37
	v_cvt_pk_bf16_f32 v35, v38, v39
	ds_read2_b64 v[36:39], v48 offset0:4 offset1:6
	s_waitcnt lgkmcnt(0)
	v_mfma_f32_32x32x16_bf16 v[0:15], v[36:39], v[32:35], v[0:15]
	ds_read2_b64 v[36:39], v49 offset0:36 offset1:38
	v_mfma_f32_32x32x16_bf16 v[16:31], v[44:47], v[40:43], v[16:31]
	s_waitcnt lgkmcnt(0)
	v_mfma_f32_32x32x16_bf16 v[16:31], v[36:39], v[32:35], v[16:31]
	v_div_scale_f32 v32, s[68:69], v96, v96, 1.0
	v_rcp_f32_e32 v33, v32
	s_nop 0
	v_fma_f32 v34, -v32, v33, 1.0
	v_fmac_f32_e32 v33, v34, v33
	v_div_scale_f32 v34, vcc, 1.0, v96, 1.0
	v_mul_f32_e32 v35, v34, v33
	v_fma_f32 v36, -v32, v35, v34
	v_fmac_f32_e32 v35, v36, v33
	v_fma_f32 v32, -v32, v35, v34
	v_div_fmas_f32 v32, v32, v33, v35
	v_div_fixup_f32 v34, v32, v96, 1.0
	v_mul_f32_e32 v0, v0, v34
	v_mul_f32_e32 v1, v1, v34
	v_cvt_pk_bf16_f32 v0, v0, v1
	v_mul_f32_e32 v1, v2, v34
	v_mad_i64_i32 v[32:33], s[68:69], v153, s65, v[116:117]
	v_and_b32_e32 v36, 63, v251
	v_and_b32_e32 v35, 31, v251
	v_lshrrev_b32_e32 v37, 5, v36
	v_lshlrev_b32_e32 v37, 3, v37
	s_movk_i32 s58, 0x90
	v_mad_u32_u24 v35, v35, s58, v37
	s_movk_i32 s59, 0x1200
	v_mad_u32_u24 v35, v254, s59, v35
	v_add_u32_e32 v35, 0x12000, v35
	v_lshrrev_b32_e32 v37, 3, v36
	v_and_b32_e32 v40, 7, v36
	v_lshlrev_b32_e32 v40, 4, v40
	v_mad_u32_u24 v36, v37, s58, v40
	v_mad_u32_u24 v36, v254, s59, v36
	v_add_u32_e32 v36, 0x12000, v36
	s_movk_i32 s58, 0xc00
	v_mad_u32_u24 v37, v37, s58, v40
	v_readfirstlane_b32 s56, v32
	v_readfirstlane_b32 s57, v33
	v_mul_f32_e32 v2, v3, v34
	v_cvt_pk_bf16_f32 v1, v1, v2
	ds_write_b64 v35, v[0:1]
	v_mul_f32_e32 v0, v4, v34
	v_mul_f32_e32 v1, v5, v34
	v_cvt_pk_bf16_f32 v0, v0, v1
	v_mul_f32_e32 v1, v6, v34
	v_mul_f32_e32 v2, v7, v34
	v_cvt_pk_bf16_f32 v1, v1, v2
	ds_write_b64 v35, v[0:1] offset:16
	v_mul_f32_e32 v0, v8, v34
	v_mul_f32_e32 v1, v9, v34
	v_cvt_pk_bf16_f32 v0, v0, v1
	v_mul_f32_e32 v1, v10, v34
	v_mul_f32_e32 v2, v11, v34
	v_cvt_pk_bf16_f32 v1, v1, v2
	ds_write_b64 v35, v[0:1] offset:32
	v_mul_f32_e32 v0, v12, v34
	v_mul_f32_e32 v1, v13, v34
	v_cvt_pk_bf16_f32 v0, v0, v1
	v_mul_f32_e32 v1, v14, v34
	v_mul_f32_e32 v2, v15, v34
	v_cvt_pk_bf16_f32 v1, v1, v2
	ds_write_b64 v35, v[0:1] offset:48
	v_mul_f32_e32 v0, v16, v34
	v_mul_f32_e32 v1, v17, v34
	v_cvt_pk_bf16_f32 v0, v0, v1
	v_mul_f32_e32 v1, v18, v34
	v_mul_f32_e32 v2, v19, v34
	v_cvt_pk_bf16_f32 v1, v1, v2
	ds_write_b64 v35, v[0:1] offset:64
	v_mul_f32_e32 v0, v20, v34
	v_mul_f32_e32 v1, v21, v34
	v_cvt_pk_bf16_f32 v0, v0, v1
	v_mul_f32_e32 v1, v22, v34
	v_mul_f32_e32 v2, v23, v34
	v_cvt_pk_bf16_f32 v1, v1, v2
	ds_write_b64 v35, v[0:1] offset:80
	v_mul_f32_e32 v0, v24, v34
	v_mul_f32_e32 v1, v25, v34
	v_cvt_pk_bf16_f32 v0, v0, v1
	v_mul_f32_e32 v1, v26, v34
	v_mul_f32_e32 v2, v27, v34
	v_cvt_pk_bf16_f32 v1, v1, v2
	ds_write_b64 v35, v[0:1] offset:96
	v_mul_f32_e32 v0, v28, v34
	v_mul_f32_e32 v1, v29, v34
	v_cvt_pk_bf16_f32 v0, v0, v1
	v_mul_f32_e32 v1, v30, v34
	s_andn2_b64 vcc, exec, s[76:77]
	v_mul_f32_e32 v2, v31, v34
	v_cvt_pk_bf16_f32 v1, v1, v2
	ds_write_b64 v35, v[0:1] offset:112
	s_waitcnt lgkmcnt(0)
	ds_read_b128 v[0:3], v36
	ds_read_b128 v[4:7], v36 offset:1152
	ds_read_b128 v[8:11], v36 offset:2304
	ds_read_b128 v[12:15], v36 offset:3456
	s_waitcnt lgkmcnt(3)
	global_store_dwordx4 v37, v[0:3], s[56:57]
	s_add_u32 s56, s56, 0x6000
	s_addc_u32 s57, s57, 0
	s_waitcnt lgkmcnt(2)
	global_store_dwordx4 v37, v[4:7], s[56:57]
	s_add_u32 s56, s56, 0x6000
	s_addc_u32 s57, s57, 0
	s_waitcnt lgkmcnt(1)
	global_store_dwordx4 v37, v[8:11], s[56:57]
	s_add_u32 s56, s56, 0x6000
	s_addc_u32 s57, s57, 0
	s_waitcnt lgkmcnt(0)
	global_store_dwordx4 v37, v[12:15], s[56:57]
	s_nop 1
	s_setprio 0
	s_cbranch_vccz .Lattn_exit
.LBB0_348:
	ds_read_b128 v[24:27], v242 offset:16
	ds_read_b128 v[28:31], v242 offset:144
	s_bfe_u32 s88, s33, 0x40002
	s_lshl_b32 s68, s88, 7
	v_add_u32_e32 v0, s68, v186
	v_max_i32_e32 v0, 0, v0
	v_lshlrev_b32_e32 v96, 7, v0
	v_lshl_add_u64 v[48:49], v[142:143], 0, v[96:97]
	v_lshl_add_u64 v[98:99], v[144:145], 0, v[96:97]
	s_add_i32 s58, s68, 0xffffff80
	v_add_u32_e32 v230, s58, v250
	v_lshl_add_u32 v230, v230, 7, v248
	v_max_i32_e32 v231, v248, v230
	global_load_dwordx4 v[116:119], v231, s[82:83]
	global_load_dwordx4 v[154:157], v231, s[92:93]
	v_add_u32_e32 v230, 0x400, v230
	v_max_i32_e32 v231, v248, v230
	global_load_dwordx4 v[44:47], v231, s[82:83]
	global_load_dwordx4 v[68:71], v231, s[92:93]
	v_add_u32_e32 v230, 0x400, v230
	v_max_i32_e32 v231, v248, v230
	global_load_dwordx4 v[158:161], v231, s[82:83]
	global_load_dwordx4 v[162:165], v231, s[92:93]
	v_add_u32_e32 v230, 0x400, v230
	v_max_i32_e32 v231, v248, v230
	global_load_dwordx4 v[40:43], v231, s[82:83]
	global_load_dwordx4 v[48:51], v231, s[92:93]
	ds_read_b128 v[72:75], v242
	ds_read_b128 v[16:19], v242 offset:48
	ds_read_b128 v[32:35], v242 offset:32
	ds_read_b128 v[20:23], v242 offset:176
	ds_read_b128 v[36:39], v242 offset:160
	ds_read_b128 v[76:79], v242 offset:128
	s_mov_b32 s0, s97
	s_and_b32 s97, s90, 12
	s_and_b32 s89, s96, 0xfffff800
	v_readlane_b32 s55, v255, 14
	s_waitcnt vmcnt(12)
	v_and_b32_e32 v224, 63, v251
	v_lshrrev_b32_e32 v225, 3, v224
	s_movk_i32 s58, 0x90
	v_mul_u32_u24_e32 v226, 0x1200, v254
	v_add_u32_e32 v226, 0x12000, v226
	v_and_b32_e32 v227, 7, v224
	v_lshlrev_b32_e32 v227, 4, v227
	v_mad_u32_u24 v227, v225, s58, v227
	v_add_u32_e32 v227, v227, v226
	v_lshrrev_b32_e32 v225, 1, v224
	v_and_b32_e32 v224, 1, v224
	v_lshlrev_b32_e32 v224, 5, v224
	v_mad_u32_u24 v224, v225, s58, v224
	v_add_u32_e32 v224, v224, v226
	ds_write_b128 v227, v[80:83]
	ds_write_b128 v227, v[84:87] offset:1152
	ds_write_b128 v227, v[88:91] offset:2304
	ds_write_b128 v227, v[92:95] offset:3456
	ds_read_b128 v[80:83], v224
	ds_read_b128 v[84:87], v224 offset:16
	ds_read_b128 v[92:95], v224 offset:64
	ds_read_b128 v[88:91], v224 offset:80
	s_waitcnt lgkmcnt(0)
	v_and_b32_e32 v64, 0xffff0000, v84
	v_lshlrev_b32_e32 v65, 16, v84
	v_and_b32_e32 v60, 0xffff0000, v85
	v_lshlrev_b32_e32 v61, 16, v85
	s_add_i32 s97, s97, s55
	v_or_b32_e32 v8, s89, v185
	v_and_b32_e32 v66, 0xffff0000, v88
	v_lshlrev_b32_e32 v67, 16, v88
	v_and_b32_e32 v62, 0xffff0000, v89
	v_lshlrev_b32_e32 v63, 16, v89
	v_pk_mul_f32 v[0:1], v[64:65], v[64:65]
	v_pk_mul_f32 v[2:3], v[60:61], v[60:61]
	v_or_b32_e32 v8, s68, v8
	s_lshl_b32 s94, s97, 7
	v_and_b32_e32 v56, 0xffff0000, v86
	v_lshlrev_b32_e32 v57, 16, v86
	v_and_b32_e32 v52, 0xffff0000, v87
	v_lshlrev_b32_e32 v53, 16, v87
	v_pk_fma_f32 v[214:215], v[66:67], v[66:67], v[0:1]
	v_pk_fma_f32 v[216:217], v[62:63], v[62:63], v[2:3]
	v_or_b32_e32 v2, 32, v8
	v_and_b32_e32 v58, 0xffff0000, v90
	v_lshlrev_b32_e32 v59, 16, v90
	v_and_b32_e32 v54, 0xffff0000, v91
	v_lshlrev_b32_e32 v55, 16, v91
	v_pk_mul_f32 v[4:5], v[56:57], v[56:57]
	v_pk_mul_f32 v[6:7], v[52:53], v[52:53]
	v_pk_fma_f32 v[218:219], v[58:59], v[58:59], v[4:5]
	v_pk_fma_f32 v[220:221], v[54:55], v[54:55], v[6:7]
	v_readlane_b32 s78, v255, 6
	v_readlane_b32 s79, v255, 7
	s_or_b32 s58, s89, s68
	s_or_b32 s58, s58, s91
	v_and_b32_e32 v231, 7, v250
	v_add_u32_e32 v231, s58, v231
	v_add_u32_e32 v230, s94, v248
	v_mad_u32_u24 v230, v231, s65, v230
	s_nop 0
	global_load_dwordx4 v[0:3], v230, s[78:79]
	v_add_u32_e32 v230, 0x6000, v230
	global_load_dwordx4 v[4:7], v230, s[78:79]
	v_add_u32_e32 v230, 0x6000, v230
	global_load_dwordx4 v[8:11], v230, s[78:79]
	v_add_u32_e32 v230, 0x6000, v230
	global_load_dwordx4 v[12:15], v230, s[78:79]
	v_add_u32_e32 v230, 0x6000, v230
	global_load_dwordx4 v[100:103], v230, s[78:79]
	v_add_u32_e32 v230, 0x6000, v230
	global_load_dwordx4 v[104:107], v230, s[78:79]
	v_add_u32_e32 v230, 0x6000, v230
	global_load_dwordx4 v[108:111], v230, s[78:79]
	v_add_u32_e32 v230, 0x6000, v230
	global_load_dwordx4 v[112:115], v230, s[78:79]
	v_lshlrev_b32_e32 v239, 16, v92
	v_lshlrev_b32_e32 v238, 16, v80
	v_and_b32_e32 v245, 0xffff0000, v92
	v_and_b32_e32 v244, 0xffff0000, v80
	v_lshlrev_b32_e32 v229, 16, v93
	v_lshlrev_b32_e32 v228, 16, v81
	v_pk_mul_f32 v[240:241], v[238:239], v[238:239]
	v_pk_mul_f32 v[246:247], v[244:245], v[244:245]
	v_pk_mul_f32 v[230:231], v[228:229], v[228:229]
	v_and_b32_e32 v235, 0xffff0000, v93
	v_and_b32_e32 v234, 0xffff0000, v81
	v_lshlrev_b32_e32 v171, 16, v94
	v_lshlrev_b32_e32 v170, 16, v82
	v_pk_mul_f32 v[236:237], v[234:235], v[234:235]
	v_and_b32_e32 v173, 0xffff0000, v94
	v_and_b32_e32 v172, 0xffff0000, v82
	v_pk_mul_f32 v[178:179], v[170:171], v[170:171]
	v_lshlrev_b32_e32 v167, 16, v95
	v_lshlrev_b32_e32 v166, 16, v83
	v_pk_mul_f32 v[180:181], v[172:173], v[172:173]
	v_and_b32_e32 v169, 0xffff0000, v95
	v_and_b32_e32 v168, 0xffff0000, v83
	v_pk_mul_f32 v[174:175], v[166:167], v[166:167]
	v_pk_mul_f32 v[176:177], v[168:169], v[168:169]
	v_readlane_b32 s76, v255, 1
	s_add_i32 s33, s33, s76
	v_readlane_b32 s77, v255, 2
	s_cmpk_gt_i32 s33, 0x3ff
	s_cselect_b64 s[76:77], -1, 0
	s_waitcnt lgkmcnt(0)
	v_mov_b32_e32 v98, v26
	s_waitcnt lgkmcnt(0)
	v_mov_b32_e32 v223, v28
	v_add_f32_e32 v26, v247, v246
	v_add_f32_e32 v28, v241, v240
	v_add_f32_e32 v26, v28, v26
	v_add_f32_e32 v28, v231, v230
	v_mov_b32_e32 v222, v24
	v_add_f32_e32 v24, v237, v236
	v_add_f32_e32 v26, v28, v26
	v_add_f32_e32 v24, v24, v26
	v_add_f32_e32 v26, v179, v178
	v_add_f32_e32 v24, v26, v24
	v_add_f32_e32 v26, v181, v180
	v_add_f32_e32 v24, v26, v24
	v_add_f32_e32 v26, v175, v174
	v_add_f32_e32 v24, v26, v24
	v_add_f32_e32 v26, v177, v176
	v_add_f32_e32 v24, v26, v24
	v_add_f32_e32 v24, v215, v24
	v_add_f32_e32 v24, v214, v24
	v_add_f32_e32 v24, v217, v24
	v_add_f32_e32 v24, v216, v24
	v_add_f32_e32 v24, v219, v24
	v_add_f32_e32 v24, v218, v24
	v_add_f32_e32 v24, v221, v24
	v_add_f32_e32 v24, v220, v24
	ds_bpermute_b32 v26, v187, v24
	s_waitcnt vmcnt(8)
	ds_write_b128 v227, v[116:119]
	ds_write_b128 v227, v[44:47] offset:1152
	ds_write_b128 v227, v[158:161] offset:2304
	ds_write_b128 v227, v[40:43] offset:3456
	v_and_b32_e32 v225, 63, v251
	v_lshrrev_b32_e32 v224, 1, v225
	v_and_b32_e32 v225, 1, v225
	v_lshlrev_b32_e32 v225, 6, v225
	v_mul_u32_u24_e32 v224, 0x90, v224
	v_add3_u32 v225, v224, v225, v226
	ds_read_b128 v[116:119], v225
	ds_read_b128 v[44:47], v225 offset:16
	ds_read_b128 v[158:161], v225 offset:32
	ds_read_b128 v[40:43], v225 offset:48
	ds_write_b128 v227, v[154:157]
	ds_write_b128 v227, v[68:71] offset:1152
	ds_write_b128 v227, v[162:165] offset:2304
	ds_write_b128 v227, v[48:51] offset:3456
	ds_read_b128 v[154:157], v225
	ds_read_b128 v[68:71], v225 offset:16
	ds_read_b128 v[162:165], v225 offset:32
	ds_read_b128 v[48:51], v225 offset:48
	s_waitcnt lgkmcnt(0)
	s_waitcnt lgkmcnt(0)
	v_mov_b32_e32 v176, v72
	s_waitcnt lgkmcnt(0)
	v_mov_b32_e32 v177, v76
	v_mov_b32_e32 v178, v116
	v_mov_b32_e32 v179, v154
	s_waitcnt lgkmcnt(0)
	v_add_f32_e32 v24, v24, v26
	v_fmamk_f32 v24, v24, 0x3c800000, v189
	v_rsq_f32_e32 v24, v24
	v_mov_b32_e32 v76, v73
	v_mov_b32_e32 v232, v74
	v_mov_b32_e32 v233, v78
	v_pk_mul_f32 v[180:181], v[24:25], v[238:239] op_sel_hi:[0,1]
	v_pk_mul_f32 v[176:177], v[176:177], v[180:181]
	v_mov_b32_e32 v174, v118
	v_pk_mul_f32 v[178:179], v[178:179], v[176:177]
	v_mov_b32_e32 v175, v156
	v_sub_f32_e32 v96, v178, v179
	v_mov_b32_e32 v178, v154
	v_mov_b32_e32 v179, v116
	v_pk_mul_f32 v[176:177], v[178:179], v[176:177]
	v_mov_b32_e32 v154, v117
	v_add_f32_e32 v153, v177, v176
	v_pk_mul_f32 v[176:177], v[24:25], v[244:245] op_sel_hi:[0,1]
	v_pk_mul_f32 v[72:73], v[76:77], v[176:177]
	v_mov_b32_e32 v116, v155
	v_pk_mul_f32 v[76:77], v[154:155], v[72:73]
	v_pk_mul_f32 v[72:73], v[116:117], v[72:73]
	v_sub_f32_e32 v154, v76, v77
	v_add_f32_e32 v116, v73, v72
	v_pk_mul_f32 v[72:73], v[24:25], v[228:229] op_sel_hi:[0,1]
	v_pk_mul_f32 v[72:73], v[232:233], v[72:73]
	v_mov_b32_e32 v78, v75
	v_pk_mul_f32 v[76:77], v[174:175], v[72:73]
	v_mov_b32_e32 v226, v44
	v_sub_f32_e32 v117, v76, v77
	v_mov_b32_e32 v76, v156
	v_mov_b32_e32 v77, v118
	v_pk_mul_f32 v[72:73], v[76:77], v[72:73]
	v_mov_b32_e32 v156, v119
	v_add_f32_e32 v76, v73, v72
	v_pk_mul_f32 v[72:73], v[24:25], v[234:235] op_sel_hi:[0,1]
	v_pk_mul_f32 v[72:73], v[78:79], v[72:73]
	v_mov_b32_e32 v118, v157
	v_pk_mul_f32 v[74:75], v[156:157], v[72:73]
	v_pk_mul_f32 v[72:73], v[118:119], v[72:73]
	v_mov_b32_e32 v227, v68
	v_add_f32_e32 v78, v73, v72
	v_pk_mul_f32 v[72:73], v[24:25], v[170:171] op_sel_hi:[0,1]
	v_pk_mul_f32 v[72:73], v[72:73], v[222:223]
	v_sub_f32_e32 v77, v74, v75
	v_pk_mul_f32 v[74:75], v[72:73], v[226:227]
	v_mov_b32_e32 v28, v25
	v_sub_f32_e32 v79, v74, v75
	v_mov_b32_e32 v74, v68
	v_mov_b32_e32 v75, v44
	v_pk_mul_f32 v[72:73], v[72:73], v[74:75]
	v_mov_b32_e32 v68, v45
	v_add_f32_e32 v74, v73, v72
	v_pk_mul_f32 v[72:73], v[24:25], v[172:173] op_sel_hi:[0,1]
	v_pk_mul_f32 v[28:29], v[72:73], v[28:29]
	v_mov_b32_e32 v44, v69
	v_pk_mul_f32 v[72:73], v[28:29], v[68:69]
	v_pk_mul_f32 v[28:29], v[28:29], v[44:45]
	v_sub_f32_e32 v25, v72, v73
	v_mov_b32_e32 v99, v30
	v_add_f32_e32 v68, v29, v28
	v_pk_mul_f32 v[28:29], v[24:25], v[166:167] op_sel_hi:[0,1]
	v_mov_b32_e32 v224, v46
	v_mov_b32_e32 v225, v70
	v_pk_mul_f32 v[28:29], v[28:29], v[98:99]
	v_mov_b32_e32 v30, v27
	v_pk_mul_f32 v[44:45], v[28:29], v[224:225]
	s_and_b64 vcc, exec, s[76:77]
	v_sub_f32_e32 v69, v44, v45
	v_mov_b32_e32 v44, v70
	v_mov_b32_e32 v45, v46
	v_pk_mul_f32 v[28:29], v[28:29], v[44:45]
	v_mov_b32_e32 v70, v47
	v_add_f32_e32 v44, v29, v28
	v_pk_mul_f32 v[28:29], v[24:25], v[168:169] op_sel_hi:[0,1]
	v_pk_mul_f32 v[26:27], v[28:29], v[30:31]
	v_mov_b32_e32 v46, v71
	v_pk_mul_f32 v[28:29], v[26:27], v[70:71]
	v_pk_mul_f32 v[26:27], v[26:27], v[46:47]
	v_sub_f32_e32 v30, v28, v29
	v_add_f32_e32 v31, v27, v26
	v_mov_b32_e32 v26, v65
	v_mov_b32_e32 v27, v67
	v_pk_mul_f32 v[26:27], v[24:25], v[26:27] op_sel_hi:[0,1]
	v_mov_b32_e32 v28, v32
	v_mov_b32_e32 v29, v36
	v_pk_mul_f32 v[26:27], v[26:27], v[28:29]
	v_mov_b32_e32 v28, v158
	v_mov_b32_e32 v29, v162
	v_pk_mul_f32 v[28:29], v[26:27], v[28:29]
	v_mov_b32_e32 v65, v66
	v_sub_f32_e32 v32, v28, v29
	v_mov_b32_e32 v28, v162
	v_mov_b32_e32 v29, v158
	v_pk_mul_f32 v[26:27], v[26:27], v[28:29]
	v_mov_b32_e32 v36, v33
	v_add_f32_e32 v45, v27, v26
	v_pk_mul_f32 v[26:27], v[24:25], v[64:65] op_sel_hi:[0,1]
	v_pk_mul_f32 v[26:27], v[26:27], v[36:37]
	v_mov_b32_e32 v162, v159
	v_mov_b32_e32 v158, v163
	v_pk_mul_f32 v[28:29], v[26:27], v[162:163]
	v_pk_mul_f32 v[26:27], v[26:27], v[158:159]
	v_sub_f32_e32 v33, v28, v29
	v_add_f32_e32 v36, v27, v26
	v_mov_b32_e32 v26, v61
	v_mov_b32_e32 v27, v63
	v_pk_mul_f32 v[26:27], v[24:25], v[26:27] op_sel_hi:[0,1]
	v_mov_b32_e32 v28, v34
	v_mov_b32_e32 v29, v38
	v_pk_mul_f32 v[26:27], v[26:27], v[28:29]
	v_mov_b32_e32 v28, v160
	v_mov_b32_e32 v29, v164
	v_pk_mul_f32 v[28:29], v[26:27], v[28:29]
	v_mov_b32_e32 v61, v62
	v_sub_f32_e32 v34, v28, v29
	v_mov_b32_e32 v28, v164
	v_mov_b32_e32 v29, v160
	v_pk_mul_f32 v[26:27], v[26:27], v[28:29]
	v_mov_b32_e32 v38, v35
	v_add_f32_e32 v37, v27, v26
	v_pk_mul_f32 v[26:27], v[24:25], v[60:61] op_sel_hi:[0,1]
	v_pk_mul_f32 v[26:27], v[26:27], v[38:39]
	v_mov_b32_e32 v164, v161
	v_mov_b32_e32 v160, v165
	v_pk_mul_f32 v[28:29], v[26:27], v[164:165]
	v_pk_mul_f32 v[26:27], v[26:27], v[160:161]
	v_sub_f32_e32 v35, v28, v29
	v_add_f32_e32 v38, v27, v26
	v_mov_b32_e32 v26, v57
	v_mov_b32_e32 v27, v59
	v_pk_mul_f32 v[26:27], v[24:25], v[26:27] op_sel_hi:[0,1]
	v_mov_b32_e32 v28, v16
	v_mov_b32_e32 v29, v20
	v_pk_mul_f32 v[26:27], v[26:27], v[28:29]
	v_mov_b32_e32 v28, v40
	v_mov_b32_e32 v29, v48
	v_pk_mul_f32 v[28:29], v[26:27], v[28:29]
	v_mov_b32_e32 v57, v58
	v_sub_f32_e32 v39, v28, v29
	v_mov_b32_e32 v28, v48
	v_mov_b32_e32 v29, v40
	v_pk_mul_f32 v[26:27], v[26:27], v[28:29]
	v_mov_b32_e32 v20, v17
	v_add_f32_e32 v28, v27, v26
	v_pk_mul_f32 v[26:27], v[24:25], v[56:57] op_sel_hi:[0,1]
	v_pk_mul_f32 v[16:17], v[26:27], v[20:21]
	v_mov_b32_e32 v48, v41
	v_mov_b32_e32 v40, v49
	v_pk_mul_f32 v[20:21], v[16:17], v[48:49]
	v_pk_mul_f32 v[16:17], v[16:17], v[40:41]
	v_sub_f32_e32 v26, v20, v21
	v_add_f32_e32 v27, v17, v16
	v_mov_b32_e32 v16, v53
	v_mov_b32_e32 v17, v55
	v_pk_mul_f32 v[16:17], v[24:25], v[16:17] op_sel_hi:[0,1]
	v_mov_b32_e32 v20, v18
	v_mov_b32_e32 v21, v22
	v_pk_mul_f32 v[16:17], v[16:17], v[20:21]
	v_mov_b32_e32 v20, v42
	v_mov_b32_e32 v21, v50
	v_pk_mul_f32 v[20:21], v[16:17], v[20:21]
	v_mov_b32_e32 v53, v54
	v_sub_f32_e32 v29, v20, v21
	v_mov_b32_e32 v20, v50
	v_mov_b32_e32 v21, v42
	v_pk_mul_f32 v[16:17], v[16:17], v[20:21]
	v_mov_b32_e32 v22, v19
	v_add_f32_e32 v20, v17, v16
	v_pk_mul_f32 v[16:17], v[24:25], v[52:53] op_sel_hi:[0,1]
	v_pk_mul_f32 v[16:17], v[16:17], v[22:23]
	v_mov_b32_e32 v50, v43
	v_mov_b32_e32 v42, v51
	v_pk_mul_f32 v[18:19], v[16:17], v[50:51]
	v_pk_mul_f32 v[16:17], v[16:17], v[42:43]
	v_sub_f32_e32 v21, v18, v19
	v_add_f32_e32 v22, v17, v16
	v_cvt_pk_bf16_f32 v16, v96, v154
	v_cvt_pk_bf16_f32 v17, v117, v77
	v_cvt_pk_bf16_f32 v18, v79, v25
	v_cvt_pk_bf16_f32 v19, v69, v30
	s_barrier
	ds_write_b128 v190, v[16:19]
	v_cvt_pk_bf16_f32 v16, v32, v33
	v_cvt_pk_bf16_f32 v17, v34, v35
	v_cvt_pk_bf16_f32 v18, v39, v26
	v_cvt_pk_bf16_f32 v19, v29, v21
	ds_write_b128 v190, v[16:19] offset:16
	v_cvt_pk_bf16_f32 v16, v153, v116
	v_cvt_pk_bf16_f32 v17, v76, v78
	v_cvt_pk_bf16_f32 v18, v74, v68
	v_cvt_pk_bf16_f32 v19, v44, v31
	ds_write_b128 v190, v[16:19] offset:64
	v_cvt_pk_bf16_f32 v16, v45, v36
	v_cvt_pk_bf16_f32 v17, v37, v38
	v_cvt_pk_bf16_f32 v18, v28, v27
	v_cvt_pk_bf16_f32 v19, v20, v22
	ds_write_b128 v190, v[16:19] offset:80
	v_and_b32_e32 v20, 63, v251
	v_lshrrev_b32_e32 v21, 3, v20
	v_mul_u32_u24_e32 v21, 0x90, v21
	v_and_b32_e32 v22, 7, v20
	v_lshl_add_u32 v21, v22, 4, v21
	v_mul_u32_u24_e32 v22, 0x1200, v254
	v_add_u32_e32 v22, 0x12000, v22
	v_add_u32_e32 v21, v21, v22
	v_lshrrev_b32_e32 v23, 2, v20
	v_mul_u32_u24_e32 v23, 0x120, v23
	v_and_b32_e32 v20, 3, v20
	v_lshl_add_u32 v23, v20, 3, v23
	v_add_u32_e32 v23, v23, v22
	ds_write_b128 v21, v[122:125]
	ds_write_b128 v21, v[128:131] offset:1152
	ds_write_b128 v21, v[132:135] offset:2304
	ds_write_b128 v21, v[136:139] offset:3456
	ds_read_b64 v[122:123], v23
	ds_read_b64 v[124:125], v23 offset:32
	ds_read_b64 v[128:129], v23 offset:64
	ds_read_b64 v[130:131], v23 offset:96
	ds_read_b64 v[132:133], v23 offset:144
	ds_read_b64 v[136:137], v23 offset:176
	ds_read_b64 v[138:139], v23 offset:208
	ds_read_b64 v[140:141], v23 offset:240
	s_waitcnt lgkmcnt(0)
	v_and_b32_e32 v16, 0xffff, v122
	v_lshrrev_b32_e32 v17, 16, v122
	v_lshl_or_b32 v16, v132, 16, v16
	v_and_or_b32 v17, v132, s54, v17
	v_add_u32_e32 v18, 0x9000, v191
	ds_write2_b32 v18, v16, v17 offset1:130
	v_and_b32_e32 v16, 0xffff, v123
	v_lshrrev_b32_e32 v17, 16, v123
	v_lshl_or_b32 v16, v133, 16, v16
	v_and_or_b32 v17, v133, s54, v17
	v_add_u32_e32 v18, 0x9400, v191
	ds_write2_b32 v18, v16, v17 offset0:4 offset1:134
	v_and_b32_e32 v16, 0xffff, v124
	v_lshrrev_b32_e32 v17, 16, v124
	v_lshl_or_b32 v16, v136, 16, v16
	v_and_or_b32 v17, v136, s54, v17
	v_add_u32_e32 v18, 0xb000, v191
	ds_write2_b32 v18, v16, v17 offset0:32 offset1:162
	v_and_b32_e32 v16, 0xffff, v125
	v_lshrrev_b32_e32 v17, 16, v125
	v_lshl_or_b32 v16, v137, 16, v16
	v_and_or_b32 v17, v137, s54, v17
	v_add_u32_e32 v18, 0xb400, v191
	ds_write2_b32 v18, v16, v17 offset0:36 offset1:166
	v_and_b32_e32 v16, 0xffff, v128
	v_lshrrev_b32_e32 v17, 16, v128
	v_lshl_or_b32 v16, v138, 16, v16
	v_and_or_b32 v17, v138, s54, v17
	v_add_u32_e32 v18, 0xd000, v191
	ds_write2_b32 v18, v16, v17 offset0:64 offset1:194
	v_and_b32_e32 v16, 0xffff, v129
	v_lshrrev_b32_e32 v17, 16, v129
	v_lshl_or_b32 v16, v139, 16, v16
	v_and_or_b32 v17, v139, s54, v17
	v_add_u32_e32 v18, 0xd400, v191
	ds_write2_b32 v18, v16, v17 offset0:68 offset1:198
	v_and_b32_e32 v16, 0xffff, v130
	v_lshrrev_b32_e32 v17, 16, v130
	v_lshl_or_b32 v16, v140, 16, v16
	v_and_or_b32 v17, v140, s54, v17
	v_add_u32_e32 v18, 0xf000, v191
	ds_write2_b32 v18, v16, v17 offset0:96 offset1:226
	v_and_b32_e32 v16, 0xffff, v131
	v_lshrrev_b32_e32 v17, 16, v131
	v_lshl_or_b32 v16, v141, 16, v16
	v_and_or_b32 v17, v141, s54, v17
	v_add_u32_e32 v18, 0xf400, v191
	ds_write2_b32 v18, v16, v17 offset0:100 offset1:230
	s_waitcnt vmcnt(0)
	v_and_b32_e32 v16, 63, v251
	v_lshrrev_b32_e32 v17, 3, v16
	v_mul_u32_u24_e32 v17, 0x90, v17
	v_and_b32_e32 v18, 7, v16
	v_lshl_add_u32 v17, v18, 4, v17
	v_mul_u32_u24_e32 v18, 0x1200, v254
	v_add_u32_e32 v18, 0x12000, v18
	v_add_u32_e32 v17, v17, v18
	v_and_b32_e32 v19, 31, v16
	v_mul_u32_u24_e32 v19, 0x90, v19
	v_lshrrev_b32_e32 v16, 5, v16
	v_lshl_add_u32 v19, v16, 4, v19
	v_add_u32_e32 v19, v19, v18
	ds_write_b128 v17, v[0:3]
	ds_write_b128 v17, v[4:7] offset:1152
	ds_write_b128 v17, v[8:11] offset:2304
	ds_write_b128 v17, v[12:15] offset:3456
	ds_read_b128 v[0:3], v19
	ds_read_b128 v[8:11], v19 offset:32
	ds_read_b128 v[4:7], v19 offset:64
	ds_read_b128 v[12:15], v19 offset:96
	ds_write_b128 v17, v[100:103]
	ds_write_b128 v17, v[104:107] offset:1152
	ds_write_b128 v17, v[108:111] offset:2304
	ds_write_b128 v17, v[112:115] offset:3456
	ds_read_b128 v[100:103], v19
	ds_read_b128 v[108:111], v19 offset:32
	ds_read_b128 v[104:107], v19 offset:64
	ds_read_b128 v[112:115], v19 offset:96
	s_waitcnt lgkmcnt(0)
	s_barrier
	s_cbranch_vccnz .LBB0_354
	s_add_i32 s64, s1, s96
	s_and_b32 s64, s64, 0x780
	s_addk_i32 s64, 0xff80
	v_mov_b32_e32 v96, v97
	v_add_u32_e32 v16, s64, v182
	v_mov_b32_e32 v98, v97
	v_mov_b32_e32 v99, v97
	v_mov_b64_e32 v[80:81], v[96:97]
	v_mov_b64_e32 v[84:85], v[96:97]
	v_mov_b64_e32 v[92:93], v[96:97]
	v_mov_b64_e32 v[88:89], v[96:97]
	s_ashr_i32 s55, s33, 6
	s_and_b32 s69, s33, 3
	v_cmp_lt_i32_e32 vcc, -1, v16
	v_mov_b64_e32 v[82:83], v[98:99]
	v_mov_b64_e32 v[86:87], v[98:99]
	v_mov_b64_e32 v[94:95], v[98:99]
	v_mov_b64_e32 v[90:91], v[98:99]
	s_and_saveexec_b64 s[78:79], vcc
	s_cbranch_execz .LBB0_351
	v_readlane_b32 vcc_lo, v255, 6
	v_readlane_b32 vcc_hi, v255, 7
	v_add_u32_e32 v18, s64, v250
	v_lshl_add_u32 v18, s55, 11, v18
	s_lshl_b32 s94, s69, 7
	v_mov_b64_e32 v[16:17], vcc
	v_mad_i64_i32 v[16:17], vcc, v18, s65, v[16:17]
	v_lshl_add_u64 v[16:17], v[16:17], 0, s[94:95]
	v_mov_b32_e32 v153, v97
	v_lshl_add_u64 v[16:17], v[16:17], 0, v[248:249]
	s_movk_i32 s94, 0x6000
	global_load_dwordx4 v[80:83], v[16:17], off offset:2048
	v_lshl_add_u64 v[16:17], v[16:17], 0, s[94:95]
	global_load_dwordx4 v[84:87], v[16:17], off offset:2048
	v_lshl_add_u64 v[16:17], v[16:17], 0, s[94:95]
	global_load_dwordx4 v[88:91], v[16:17], off offset:2048
	v_lshl_add_u64 v[16:17], v[16:17], 0, s[94:95]
	global_load_dwordx4 v[92:95], v[16:17], off offset:2048

.Lattn_exit:
	s_barrier
	s_branch .LBB0_359
